# speedup vs baseline: 1.0087x; 1.0087x over previous
.LBB0_678:
	v_bfe_u32 v136, v182, 4, 1
	v_mul_u32_u24_e32 v136, 24, v136
	v_add_u32_e32 v136, v0, v136
	v_mov_b32_e32 v137, 0
	v_mul_f32_e32 v132, 0xbfb8aa3b, v126
	v_exp_f32_e32 v132, v132
	s_mul_hi_i32 s2, s20, 0x160000
	s_mul_i32 s20, s20, 0x160000
	s_add_u32 s22, s92, s20
	v_add_f32_e32 v132, 1.0, v132
	v_rcp_f32_e32 v132, v132
	s_addc_u32 s2, s93, s2
	s_lshl_b32 s20, s21, 7
	s_ashr_i32 s21, s20, 31
	v_mul_f32_e32 v126, v126, v132
	v_mul_f32_e32 v122, v122, v126
	v_mul_f32_e32 v126, 0xbfb8aa3b, v127
	v_exp_f32_e32 v126, v126
	s_lshl_b64 s[20:21], s[20:21], 1
	s_add_u32 s20, s22, s20
	s_addc_u32 s21, s2, s21
	v_add_f32_e32 v126, 1.0, v126
	v_rcp_f32_e32 v126, v126
	v_lshl_add_u64 v[130:131], s[20:21], 0, v[196:197]
	v_mul_f32_e32 v126, v127, v126
	v_mul_f32_e32 v123, v123, v126
	v_cvt_pk_bf16_f32 v122, v122, v123
	v_mul_f32_e32 v123, 0xbfb8aa3b, v128
	v_exp_f32_e32 v123, v123
	s_nop 0
	v_add_f32_e32 v123, 1.0, v123
	v_rcp_f32_e32 v123, v123
	s_nop 0
	v_mul_f32_e32 v123, v128, v123
	v_mul_f32_e32 v123, v124, v123
	v_mul_f32_e32 v124, 0xbfb8aa3b, v129
	v_exp_f32_e32 v124, v124
	s_nop 0
	v_add_f32_e32 v124, 1.0, v124
	v_rcp_f32_e32 v124, v124
	s_nop 0
	v_mul_f32_e32 v124, v129, v124
	v_mul_f32_e32 v124, v125, v124
	v_cvt_pk_bf16_f32 v123, v123, v124
	v_lshl_add_u64 v[134:135], v[130:131], 0, v[136:137]
	v_mul_f32_e32 v138, 0xbfb8aa3b, v118
	v_exp_f32_e32 v138, v138
	s_nop 0
	v_add_f32_e32 v138, 1.0, v138
	v_rcp_f32_e32 v138, v138
	s_nop 0
	v_mul_f32_e32 v118, v118, v138
	v_mul_f32_e32 v114, v114, v118
	v_mul_f32_e32 v118, 0xbfb8aa3b, v119
	v_exp_f32_e32 v118, v118
	s_nop 0
	v_add_f32_e32 v118, 1.0, v118
	v_rcp_f32_e32 v118, v118
	s_nop 0
	v_mul_f32_e32 v118, v119, v118
	v_mul_f32_e32 v115, v115, v118
	v_cvt_pk_bf16_f32 v124, v114, v115
	v_mul_f32_e32 v115, 0xbfb8aa3b, v120
	v_exp_f32_e32 v115, v115
	s_nop 0
	v_add_f32_e32 v115, 1.0, v115
	v_rcp_f32_e32 v115, v115
	s_nop 0
	v_mul_f32_e32 v115, v120, v115
	v_mul_f32_e32 v115, v116, v115
	v_mul_f32_e32 v116, 0xbfb8aa3b, v121
	v_exp_f32_e32 v116, v116
	s_nop 0
	v_add_f32_e32 v116, 1.0, v116
	v_rcp_f32_e32 v116, v116
	s_nop 0
	v_mul_f32_e32 v116, v121, v116
	v_mul_f32_e32 v116, v117, v116
	v_cvt_pk_bf16_f32 v125, v115, v116
	s_nop 1
	v_permlane16_swap_b32_e32 v122, v124
	v_permlane16_swap_b32_e32 v123, v125
	global_store_dwordx4 v[134:135], v[122:125], off
	v_mul_f32_e32 v116, 0xbfb8aa3b, v110
	v_exp_f32_e32 v116, v116
	v_lshl_add_u64 v[114:115], s[20:21], 0, v[198:199]
	v_add_f32_e32 v116, 1.0, v116
	v_rcp_f32_e32 v116, v116
	s_nop 0
	v_mul_f32_e32 v110, v110, v116
	v_mul_f32_e32 v106, v106, v110
	v_mul_f32_e32 v110, 0xbfb8aa3b, v111
	v_exp_f32_e32 v110, v110
	s_nop 0
	v_add_f32_e32 v110, 1.0, v110
	v_rcp_f32_e32 v110, v110
	s_nop 0
	v_mul_f32_e32 v110, v111, v110
	v_mul_f32_e32 v107, v107, v110
	v_cvt_pk_bf16_f32 v106, v106, v107
	v_mul_f32_e32 v107, 0xbfb8aa3b, v112
	v_exp_f32_e32 v107, v107
	s_nop 0
	v_add_f32_e32 v107, 1.0, v107
	v_rcp_f32_e32 v107, v107
	s_nop 0
	v_mul_f32_e32 v107, v112, v107
	v_mul_f32_e32 v107, v108, v107
	v_mul_f32_e32 v108, 0xbfb8aa3b, v113
	v_exp_f32_e32 v108, v108
	s_nop 0
	v_add_f32_e32 v108, 1.0, v108
	v_rcp_f32_e32 v108, v108
	s_nop 0
	v_mul_f32_e32 v108, v113, v108
	v_mul_f32_e32 v108, v109, v108
	v_cvt_pk_bf16_f32 v107, v107, v108
	v_lshl_add_u64 v[134:135], v[114:115], 0, v[136:137]
	v_mul_f32_e32 v138, 0xbfb8aa3b, v102
	v_exp_f32_e32 v138, v138
	s_nop 0
	v_add_f32_e32 v138, 1.0, v138
	v_rcp_f32_e32 v138, v138
	s_nop 0
	v_mul_f32_e32 v102, v102, v138
	v_mul_f32_e32 v98, v98, v102
	v_mul_f32_e32 v102, 0xbfb8aa3b, v103
	v_exp_f32_e32 v102, v102
	s_nop 0
	v_add_f32_e32 v102, 1.0, v102
	v_rcp_f32_e32 v102, v102
	s_nop 0
	v_mul_f32_e32 v102, v103, v102
	v_mul_f32_e32 v99, v99, v102
	v_cvt_pk_bf16_f32 v108, v98, v99
	v_mul_f32_e32 v99, 0xbfb8aa3b, v104
	v_exp_f32_e32 v99, v99
	s_nop 0
	v_add_f32_e32 v99, 1.0, v99
	v_rcp_f32_e32 v99, v99
	s_nop 0
	v_mul_f32_e32 v99, v104, v99
	v_mul_f32_e32 v99, v100, v99
	v_mul_f32_e32 v100, 0xbfb8aa3b, v105
	v_exp_f32_e32 v100, v100
	s_nop 0
	v_add_f32_e32 v100, 1.0, v100
	v_rcp_f32_e32 v100, v100
	s_nop 0
	v_mul_f32_e32 v100, v105, v100
	v_mul_f32_e32 v100, v101, v100
	v_cvt_pk_bf16_f32 v109, v99, v100
	s_nop 1
	v_permlane16_swap_b32_e32 v106, v108
	v_permlane16_swap_b32_e32 v107, v109
	global_store_dwordx4 v[134:135], v[106:109], off
	v_mul_f32_e32 v100, 0xbfb8aa3b, v94
	v_exp_f32_e32 v100, v100
	v_lshl_add_u64 v[98:99], s[20:21], 0, v[200:201]
	v_add_f32_e32 v100, 1.0, v100
	v_rcp_f32_e32 v100, v100
	s_nop 0
	v_mul_f32_e32 v94, v94, v100
	v_mul_f32_e32 v90, v90, v94
	v_mul_f32_e32 v94, 0xbfb8aa3b, v95
	v_exp_f32_e32 v94, v94
	s_nop 0
	v_add_f32_e32 v94, 1.0, v94
	v_rcp_f32_e32 v94, v94
	s_nop 0
	v_mul_f32_e32 v94, v95, v94
	v_mul_f32_e32 v91, v91, v94
	v_cvt_pk_bf16_f32 v90, v90, v91
	v_mul_f32_e32 v91, 0xbfb8aa3b, v96
	v_exp_f32_e32 v91, v91
	s_nop 0
	v_add_f32_e32 v91, 1.0, v91
	v_rcp_f32_e32 v91, v91
	s_nop 0
	v_mul_f32_e32 v91, v96, v91
	v_mul_f32_e32 v91, v92, v91
	v_mul_f32_e32 v92, 0xbfb8aa3b, v97
	v_exp_f32_e32 v92, v92
	s_nop 0
	v_add_f32_e32 v92, 1.0, v92
	v_rcp_f32_e32 v92, v92
	s_nop 0
	v_mul_f32_e32 v92, v97, v92
	v_mul_f32_e32 v92, v93, v92
	v_cvt_pk_bf16_f32 v91, v91, v92
	v_lshl_add_u64 v[134:135], v[98:99], 0, v[136:137]
	v_mul_f32_e32 v138, 0xbfb8aa3b, v86
	v_exp_f32_e32 v138, v138
	s_nop 0
	v_add_f32_e32 v138, 1.0, v138
	v_rcp_f32_e32 v138, v138
	s_nop 0
	v_mul_f32_e32 v86, v86, v138
	v_mul_f32_e32 v82, v82, v86
	v_mul_f32_e32 v86, 0xbfb8aa3b, v87
	v_exp_f32_e32 v86, v86
	s_nop 0
	v_add_f32_e32 v86, 1.0, v86
	v_rcp_f32_e32 v86, v86
	s_nop 0
	v_mul_f32_e32 v86, v87, v86
	v_mul_f32_e32 v83, v83, v86
	v_cvt_pk_bf16_f32 v92, v82, v83
	v_mul_f32_e32 v83, 0xbfb8aa3b, v88
	v_exp_f32_e32 v83, v83
	s_nop 0
	v_add_f32_e32 v83, 1.0, v83
	v_rcp_f32_e32 v83, v83
	s_nop 0
	v_mul_f32_e32 v83, v88, v83
	v_mul_f32_e32 v83, v84, v83
	v_mul_f32_e32 v84, 0xbfb8aa3b, v89
	v_exp_f32_e32 v84, v84
	s_nop 0
	v_add_f32_e32 v84, 1.0, v84
	v_rcp_f32_e32 v84, v84
	s_nop 0
	v_mul_f32_e32 v84, v89, v84
	v_mul_f32_e32 v84, v85, v84
	v_cvt_pk_bf16_f32 v93, v83, v84
	s_nop 1
	v_permlane16_swap_b32_e32 v90, v92
	v_permlane16_swap_b32_e32 v91, v93
	global_store_dwordx4 v[134:135], v[90:93], off
	v_mul_f32_e32 v84, 0xbfb8aa3b, v78
	v_exp_f32_e32 v84, v84
	v_lshl_add_u64 v[82:83], s[20:21], 0, v[202:203]
	v_add_f32_e32 v84, 1.0, v84
	v_rcp_f32_e32 v84, v84
	s_nop 0
	v_mul_f32_e32 v78, v78, v84
	v_mul_f32_e32 v74, v74, v78
	v_mul_f32_e32 v78, 0xbfb8aa3b, v79
	v_exp_f32_e32 v78, v78
	s_nop 0
	v_add_f32_e32 v78, 1.0, v78
	v_rcp_f32_e32 v78, v78
	s_nop 0
	v_mul_f32_e32 v78, v79, v78
	v_mul_f32_e32 v75, v75, v78
	v_cvt_pk_bf16_f32 v74, v74, v75
	v_mul_f32_e32 v75, 0xbfb8aa3b, v80
	v_exp_f32_e32 v75, v75
	s_nop 0
	v_add_f32_e32 v75, 1.0, v75
	v_rcp_f32_e32 v75, v75
	s_nop 0
	v_mul_f32_e32 v75, v80, v75
	v_mul_f32_e32 v75, v76, v75
	v_mul_f32_e32 v76, 0xbfb8aa3b, v81
	v_exp_f32_e32 v76, v76
	s_nop 0
	v_add_f32_e32 v76, 1.0, v76
	v_rcp_f32_e32 v76, v76
	s_nop 0
	v_mul_f32_e32 v76, v81, v76
	v_mul_f32_e32 v76, v77, v76
	v_cvt_pk_bf16_f32 v75, v75, v76
	v_lshl_add_u64 v[134:135], v[82:83], 0, v[136:137]
	v_mul_f32_e32 v138, 0xbfb8aa3b, v70
	v_exp_f32_e32 v138, v138
	s_nop 0
	v_add_f32_e32 v138, 1.0, v138
	v_rcp_f32_e32 v138, v138
	s_nop 0
	v_mul_f32_e32 v70, v70, v138
	v_mul_f32_e32 v66, v66, v70
	v_mul_f32_e32 v70, 0xbfb8aa3b, v71
	v_exp_f32_e32 v70, v70
	s_nop 0
	v_add_f32_e32 v70, 1.0, v70
	v_rcp_f32_e32 v70, v70
	s_nop 0
	v_mul_f32_e32 v70, v71, v70
	v_mul_f32_e32 v67, v67, v70
	v_cvt_pk_bf16_f32 v76, v66, v67
	v_mul_f32_e32 v67, 0xbfb8aa3b, v72
	v_exp_f32_e32 v67, v67
	s_nop 0
	v_add_f32_e32 v67, 1.0, v67
	v_rcp_f32_e32 v67, v67
	s_nop 0
	v_mul_f32_e32 v67, v72, v67
	v_mul_f32_e32 v67, v68, v67
	v_mul_f32_e32 v68, 0xbfb8aa3b, v73
	v_exp_f32_e32 v68, v68
	s_nop 0
	v_add_f32_e32 v68, 1.0, v68
	v_rcp_f32_e32 v68, v68
	s_nop 0
	v_mul_f32_e32 v68, v73, v68
	v_mul_f32_e32 v68, v69, v68
	v_cvt_pk_bf16_f32 v77, v67, v68
	s_nop 1
	v_permlane16_swap_b32_e32 v74, v76
	v_permlane16_swap_b32_e32 v75, v77
	global_store_dwordx4 v[134:135], v[74:77], off
	v_mul_f32_e32 v68, 0xbfb8aa3b, v62
	v_exp_f32_e32 v68, v68
	v_lshl_add_u64 v[66:67], s[20:21], 0, v[204:205]
	v_add_f32_e32 v68, 1.0, v68
	v_rcp_f32_e32 v68, v68
	s_nop 0
	v_mul_f32_e32 v62, v62, v68
	v_mul_f32_e32 v58, v58, v62
	v_mul_f32_e32 v62, 0xbfb8aa3b, v63
	v_exp_f32_e32 v62, v62
	s_nop 0
	v_add_f32_e32 v62, 1.0, v62
	v_rcp_f32_e32 v62, v62
	s_nop 0
	v_mul_f32_e32 v62, v63, v62
	v_mul_f32_e32 v59, v59, v62
	v_cvt_pk_bf16_f32 v58, v58, v59
	v_mul_f32_e32 v59, 0xbfb8aa3b, v64
	v_exp_f32_e32 v59, v59
	s_nop 0
	v_add_f32_e32 v59, 1.0, v59
	v_rcp_f32_e32 v59, v59
	s_nop 0
	v_mul_f32_e32 v59, v64, v59
	v_mul_f32_e32 v59, v60, v59
	v_mul_f32_e32 v60, 0xbfb8aa3b, v65
	v_exp_f32_e32 v60, v60
	s_nop 0
	v_add_f32_e32 v60, 1.0, v60
	v_rcp_f32_e32 v60, v60
	s_nop 0
	v_mul_f32_e32 v60, v65, v60
	v_mul_f32_e32 v60, v61, v60
	v_cvt_pk_bf16_f32 v59, v59, v60
	v_lshl_add_u64 v[134:135], v[66:67], 0, v[136:137]
	v_mul_f32_e32 v138, 0xbfb8aa3b, v54
	v_exp_f32_e32 v138, v138
	s_nop 0
	v_add_f32_e32 v138, 1.0, v138
	v_rcp_f32_e32 v138, v138
	s_nop 0
	v_mul_f32_e32 v54, v54, v138
	v_mul_f32_e32 v50, v50, v54
	v_mul_f32_e32 v54, 0xbfb8aa3b, v55
	v_exp_f32_e32 v54, v54
	s_nop 0
	v_add_f32_e32 v54, 1.0, v54
	v_rcp_f32_e32 v54, v54
	s_nop 0
	v_mul_f32_e32 v54, v55, v54
	v_mul_f32_e32 v51, v51, v54
	v_cvt_pk_bf16_f32 v60, v50, v51
	v_mul_f32_e32 v51, 0xbfb8aa3b, v56
	v_exp_f32_e32 v51, v51
	s_nop 0
	v_add_f32_e32 v51, 1.0, v51
	v_rcp_f32_e32 v51, v51
	s_nop 0
	v_mul_f32_e32 v51, v56, v51
	v_mul_f32_e32 v51, v52, v51
	v_mul_f32_e32 v52, 0xbfb8aa3b, v57
	v_exp_f32_e32 v52, v52
	s_nop 0
	v_add_f32_e32 v52, 1.0, v52
	v_rcp_f32_e32 v52, v52
	s_nop 0
	v_mul_f32_e32 v52, v57, v52
	v_mul_f32_e32 v52, v53, v52
	v_cvt_pk_bf16_f32 v61, v51, v52
	s_nop 1
	v_permlane16_swap_b32_e32 v58, v60
	v_permlane16_swap_b32_e32 v59, v61
	global_store_dwordx4 v[134:135], v[58:61], off
	v_mul_f32_e32 v52, 0xbfb8aa3b, v46
	v_exp_f32_e32 v52, v52
	v_lshl_add_u64 v[50:51], s[20:21], 0, v[206:207]
	v_add_f32_e32 v52, 1.0, v52
	v_rcp_f32_e32 v52, v52
	s_nop 0
	v_mul_f32_e32 v46, v46, v52
	v_mul_f32_e32 v42, v42, v46
	v_mul_f32_e32 v46, 0xbfb8aa3b, v47
	v_exp_f32_e32 v46, v46
	s_nop 0
	v_add_f32_e32 v46, 1.0, v46
	v_rcp_f32_e32 v46, v46
	s_nop 0
	v_mul_f32_e32 v46, v47, v46
	v_mul_f32_e32 v43, v43, v46
	v_cvt_pk_bf16_f32 v42, v42, v43
	v_mul_f32_e32 v43, 0xbfb8aa3b, v48
	v_exp_f32_e32 v43, v43
	s_nop 0
	v_add_f32_e32 v43, 1.0, v43
	v_rcp_f32_e32 v43, v43
	s_nop 0
	v_mul_f32_e32 v43, v48, v43
	v_mul_f32_e32 v43, v44, v43
	v_mul_f32_e32 v44, 0xbfb8aa3b, v49
	v_exp_f32_e32 v44, v44
	s_nop 0
	v_add_f32_e32 v44, 1.0, v44
	v_rcp_f32_e32 v44, v44
	s_nop 0
	v_mul_f32_e32 v44, v49, v44
	v_mul_f32_e32 v44, v45, v44
	v_cvt_pk_bf16_f32 v43, v43, v44
	v_lshl_add_u64 v[134:135], v[50:51], 0, v[136:137]
	v_mul_f32_e32 v138, 0xbfb8aa3b, v38
	v_exp_f32_e32 v138, v138
	s_nop 0
	v_add_f32_e32 v138, 1.0, v138
	v_rcp_f32_e32 v138, v138
	s_nop 0
	v_mul_f32_e32 v38, v38, v138
	v_mul_f32_e32 v34, v34, v38
	v_mul_f32_e32 v38, 0xbfb8aa3b, v39
	v_exp_f32_e32 v38, v38
	s_nop 0
	v_add_f32_e32 v38, 1.0, v38
	v_rcp_f32_e32 v38, v38
	s_nop 0
	v_mul_f32_e32 v38, v39, v38
	v_mul_f32_e32 v35, v35, v38
	v_cvt_pk_bf16_f32 v44, v34, v35
	v_mul_f32_e32 v35, 0xbfb8aa3b, v40
	v_exp_f32_e32 v35, v35
	s_nop 0
	v_add_f32_e32 v35, 1.0, v35
	v_rcp_f32_e32 v35, v35
	s_nop 0
	v_mul_f32_e32 v35, v40, v35
	v_mul_f32_e32 v35, v36, v35
	v_mul_f32_e32 v36, 0xbfb8aa3b, v41
	v_exp_f32_e32 v36, v36
	s_nop 0
	v_add_f32_e32 v36, 1.0, v36
	v_rcp_f32_e32 v36, v36
	s_nop 0
	v_mul_f32_e32 v36, v41, v36
	v_mul_f32_e32 v36, v37, v36
	v_cvt_pk_bf16_f32 v45, v35, v36
	s_nop 1
	v_permlane16_swap_b32_e32 v42, v44
	v_permlane16_swap_b32_e32 v43, v45
	global_store_dwordx4 v[134:135], v[42:45], off
	v_mul_f32_e32 v36, 0xbfb8aa3b, v30
	v_exp_f32_e32 v36, v36
	v_lshl_add_u64 v[34:35], s[20:21], 0, v[208:209]
	v_add_f32_e32 v36, 1.0, v36
	v_rcp_f32_e32 v36, v36
	s_nop 0
	v_mul_f32_e32 v30, v30, v36
	v_mul_f32_e32 v26, v26, v30
	v_mul_f32_e32 v30, 0xbfb8aa3b, v31
	v_exp_f32_e32 v30, v30
	s_nop 0
	v_add_f32_e32 v30, 1.0, v30
	v_rcp_f32_e32 v30, v30
	s_nop 0
	v_mul_f32_e32 v30, v31, v30
	v_mul_f32_e32 v27, v27, v30
	v_cvt_pk_bf16_f32 v26, v26, v27
	v_mul_f32_e32 v27, 0xbfb8aa3b, v32
	v_exp_f32_e32 v27, v27
	s_nop 0
	v_add_f32_e32 v27, 1.0, v27
	v_rcp_f32_e32 v27, v27
	s_nop 0
	v_mul_f32_e32 v27, v32, v27
	v_mul_f32_e32 v27, v28, v27
	v_mul_f32_e32 v28, 0xbfb8aa3b, v33
	v_exp_f32_e32 v28, v28
	s_nop 0
	v_add_f32_e32 v28, 1.0, v28
	v_rcp_f32_e32 v28, v28
	s_nop 0
	v_mul_f32_e32 v28, v33, v28
	v_mul_f32_e32 v28, v29, v28
	v_cvt_pk_bf16_f32 v27, v27, v28
	v_lshl_add_u64 v[134:135], v[34:35], 0, v[136:137]
	v_mul_f32_e32 v138, 0xbfb8aa3b, v22
	v_exp_f32_e32 v138, v138
	s_nop 0
	v_add_f32_e32 v138, 1.0, v138
	v_rcp_f32_e32 v138, v138
	s_nop 0
	v_mul_f32_e32 v22, v22, v138
	v_mul_f32_e32 v18, v18, v22
	v_mul_f32_e32 v22, 0xbfb8aa3b, v23
	v_exp_f32_e32 v22, v22
	s_nop 0
	v_add_f32_e32 v22, 1.0, v22
	v_rcp_f32_e32 v22, v22
	s_nop 0
	v_mul_f32_e32 v22, v23, v22
	v_mul_f32_e32 v19, v19, v22
	v_cvt_pk_bf16_f32 v28, v18, v19
	v_mul_f32_e32 v19, 0xbfb8aa3b, v24
	v_exp_f32_e32 v19, v19
	s_nop 0
	v_add_f32_e32 v19, 1.0, v19
	v_rcp_f32_e32 v19, v19
	s_nop 0
	v_mul_f32_e32 v19, v24, v19
	v_mul_f32_e32 v19, v20, v19
	v_mul_f32_e32 v20, 0xbfb8aa3b, v25
	v_exp_f32_e32 v20, v20
	s_nop 0
	v_add_f32_e32 v20, 1.0, v20
	v_rcp_f32_e32 v20, v20
	s_nop 0
	v_mul_f32_e32 v20, v25, v20
	v_mul_f32_e32 v20, v21, v20
	v_cvt_pk_bf16_f32 v29, v19, v20
	s_nop 1
	v_permlane16_swap_b32_e32 v26, v28
	v_permlane16_swap_b32_e32 v27, v29
	global_store_dwordx4 v[134:135], v[26:29], off
	v_mul_f32_e32 v20, 0xbfb8aa3b, v14
	v_exp_f32_e32 v20, v20
	v_lshl_add_u64 v[18:19], s[20:21], 0, v[210:211]
	v_add_f32_e32 v20, 1.0, v20
	v_rcp_f32_e32 v20, v20
	s_nop 0
	v_mul_f32_e32 v14, v14, v20
	v_mul_f32_e32 v10, v10, v14
	v_mul_f32_e32 v14, 0xbfb8aa3b, v15
	v_exp_f32_e32 v14, v14
	s_nop 0
	v_add_f32_e32 v14, 1.0, v14
	v_rcp_f32_e32 v14, v14
	s_nop 0
	v_mul_f32_e32 v14, v15, v14
	v_mul_f32_e32 v11, v11, v14
	v_cvt_pk_bf16_f32 v10, v10, v11
	v_mul_f32_e32 v11, 0xbfb8aa3b, v16
	v_exp_f32_e32 v11, v11
	s_nop 0
	v_add_f32_e32 v11, 1.0, v11
	v_rcp_f32_e32 v11, v11
	s_nop 0
	v_mul_f32_e32 v11, v16, v11
	v_mul_f32_e32 v11, v12, v11
	v_mul_f32_e32 v12, 0xbfb8aa3b, v17
	v_exp_f32_e32 v12, v12
	s_nop 0
	v_add_f32_e32 v12, 1.0, v12
	v_rcp_f32_e32 v12, v12
	s_nop 0
	v_mul_f32_e32 v12, v17, v12
	v_mul_f32_e32 v12, v13, v12
	v_cvt_pk_bf16_f32 v11, v11, v12
	v_lshl_add_u64 v[134:135], v[18:19], 0, v[136:137]
	v_mul_f32_e32 v138, 0xbfb8aa3b, v6
	v_exp_f32_e32 v138, v138
	s_nop 0
	v_add_f32_e32 v138, 1.0, v138
	v_rcp_f32_e32 v138, v138
	s_nop 0
	v_mul_f32_e32 v6, v6, v138
	v_mul_f32_e32 v2, v2, v6
	v_mul_f32_e32 v6, 0xbfb8aa3b, v7
	v_exp_f32_e32 v6, v6
	s_nop 0
	v_add_f32_e32 v6, 1.0, v6
	v_rcp_f32_e32 v6, v6
	s_nop 0
	v_mul_f32_e32 v6, v7, v6
	v_mul_f32_e32 v3, v3, v6
	v_cvt_pk_bf16_f32 v12, v2, v3
	v_mul_f32_e32 v3, 0xbfb8aa3b, v8
	v_exp_f32_e32 v3, v3
	s_nop 0
	v_add_f32_e32 v3, 1.0, v3
	v_rcp_f32_e32 v3, v3
	s_nop 0
	v_mul_f32_e32 v3, v8, v3
	v_mul_f32_e32 v3, v4, v3
	v_mul_f32_e32 v4, 0xbfb8aa3b, v9
	v_exp_f32_e32 v4, v4
	s_nop 0
	v_add_f32_e32 v4, 1.0, v4
	v_rcp_f32_e32 v4, v4
	s_nop 0
	v_mul_f32_e32 v4, v9, v4
	v_mul_f32_e32 v4, v5, v4
	v_cvt_pk_bf16_f32 v13, v3, v4
	s_nop 1
	v_permlane16_swap_b32_e32 v10, v12
	v_permlane16_swap_b32_e32 v11, v13
	global_store_dwordx4 v[134:135], v[10:13], off
	s_andn2_b64 vcc, exec, s[18:19]
	s_mov_b64 s[18:19], -1
	s_cbranch_vccnz .LBB0_657
	s_mov_b64 s[18:19], 0
	s_branch .LBB0_657
